# 7.12-style: row-max v_max3 serial chain before the rescale branch split into two interleaved half-chains (5 sites)
# speedup vs baseline: 1.0061x; 1.0061x over previous
; DI float fexp2(float x) { return __builtin_amdgcn_exp2f(x); }
; template <int MODE> DI void attn_h1(AttnCtx& c, const bf16x8 (&q)[8], f32x16 (&o)[4], f32x16& s0, f32x16& s1, ldsp lds, int kbuf, int bbuf, int tj, int lane) {
;     ...
;             if (MODE != MD_CMP2) {
;                 float mx = s0[0];
; #pragma unroll
;                 for (int e = 1; e < 16; ++e) mx = fmaxf(mx, s0[e]);
; #pragma unroll
;                 for (int e = 0; e < 16; ++e) mx = fmaxf(mx, s1[e]);
;                 { typedef unsigned u2_t __attribute__((ext_vector_type(2)));
;                   const unsigned mb = __builtin_bit_cast(unsigned, mx);
;                   const u2_t sw = __builtin_amdgcn_permlane32_swap(mb, mb, false, false);
;                   mx = fmaxf(__builtin_bit_cast(float, sw.x), __builtin_bit_cast(float, sw.y)); }
;                 const bool need = mx > c.m + 12.0f;
;                 if (__ballot(need) != 0ull) {
;                     const float mnew = need ? mx : c.m;
;                     const float alpha = fexp2(c.m - ((mnew == NINF) ? 0.f : mnew));
;                     c.l *= alpha; c.m = mnew;
;                     if (MODE != MD_CMP1) {
; #pragma unroll
;                         for (int db = 0; db < 4; ++db)
; #pragma unroll
;                             for (int e = 0; e < 16; ++e) o[db][e] *= alpha;
;                     }
;                 }
.LBB0_542:
	s_or_b64 exec, exec, s[2:3]
	v_max_f32_e32 v0, v83, v83
	v_max_f32_e32 v2, v82, v82
	v_max_f32_e32 v0, v2, v0
	v_max3_f32 v0, v0, v84, v85
	v_max_f32_e32 v2, v98, v99
	v_max3_f32 v0, v0, v86, v87
	v_max3_f32 v2, v2, v100, v101
	v_max3_f32 v0, v0, v88, v89
	v_max3_f32 v2, v2, v102, v103
	v_max3_f32 v0, v0, v90, v91
	v_max3_f32 v2, v2, v104, v105
	v_max3_f32 v0, v0, v92, v93
	v_max3_f32 v2, v2, v106, v107
	v_max3_f32 v0, v0, v94, v95
	v_max3_f32 v2, v2, v108, v109
	v_max3_f32 v0, v0, v96, v97
	v_max3_f32 v2, v2, v110, v111
	v_max3_f32 v2, v2, v112, v113
	v_max_f32_e32 v0, v0, v2
	v_mov_b32_e32 v2, v0
	s_nop 1
	v_permlane32_swap_b32_e32 v0, v2
	v_mov_b32_e32 v201, 0xff800000
	v_cmp_lg_f32_e64 s[2:3], v0, v201
	v_cmp_neq_f32_e32 vcc, v0, v201
	s_cbranch_vccz .LBB0_544
	v_cndmask_b32_e64 v201, v230, v0, s[2:3]
	v_sub_f32_e32 v0, 0xff800000, v201
	v_cmp_neq_f32_e32 vcc, s53, v201
	s_nop 1
	v_cndmask_b32_e32 v0, v230, v0, vcc
	v_exp_f32_e32 v0, v0
	s_nop 0
	v_mul_f32_e32 v32, 0, v0
	v_mov_b32_e32 v33, v32
	v_mov_b32_e32 v34, v32
	v_mov_b32_e32 v35, v32
	v_mov_b32_e32 v36, v32
	v_mov_b32_e32 v37, v32
	v_mov_b32_e32 v38, v32
	v_mov_b32_e32 v39, v32
	v_mov_b32_e32 v40, v32
	v_mov_b32_e32 v41, v32
	v_mov_b32_e32 v42, v32
	v_mov_b32_e32 v43, v32
	v_mov_b32_e32 v44, v32
	v_mov_b32_e32 v45, v32
	v_mov_b32_e32 v46, v32
	v_mov_b32_e32 v47, v32
	v_mov_b64_e32 v[16:17], v[32:33]
	v_mov_b64_e32 v[18:19], v[34:35]
	v_mov_b64_e32 v[20:21], v[36:37]
	v_mov_b64_e32 v[22:23], v[38:39]
	v_mov_b64_e32 v[24:25], v[40:41]
	v_mov_b64_e32 v[26:27], v[42:43]
	v_mov_b64_e32 v[28:29], v[44:45]
	v_mov_b64_e32 v[30:31], v[46:47]
	s_branch .LBB0_545

; DI float fexp2(float x) { return __builtin_amdgcn_exp2f(x); }
; template <int MODE> DI void attn_h1(AttnCtx& c, const bf16x8 (&q)[8], f32x16 (&o)[4], f32x16& s0, f32x16& s1, ldsp lds, int kbuf, int bbuf, int tj, int lane) {
;     ...
;             if (MODE != MD_CMP2) {
;                 float mx = s0[0];
; #pragma unroll
;                 for (int e = 1; e < 16; ++e) mx = fmaxf(mx, s0[e]);
; #pragma unroll
;                 for (int e = 0; e < 16; ++e) mx = fmaxf(mx, s1[e]);
;                 { typedef unsigned u2_t __attribute__((ext_vector_type(2)));
;                   const unsigned mb = __builtin_bit_cast(unsigned, mx);
;                   const u2_t sw = __builtin_amdgcn_permlane32_swap(mb, mb, false, false);
;                   mx = fmaxf(__builtin_bit_cast(float, sw.x), __builtin_bit_cast(float, sw.y)); }
;                 const bool need = mx > c.m + 12.0f;
;                 if (__ballot(need) != 0ull) {
;                     const float mnew = need ? mx : c.m;
;                     const float alpha = fexp2(c.m - ((mnew == NINF) ? 0.f : mnew));
;                     c.l *= alpha; c.m = mnew;
;                     if (MODE != MD_CMP1) {
; #pragma unroll
;                         for (int db = 0; db < 4; ++db)
; #pragma unroll
;                             for (int e = 0; e < 16; ++e) o[db][e] *= alpha;
;                     }
;                 }
.LBB0_567:
	s_or_b64 exec, exec, s[26:27]
	v_max_f32_e32 v0, v83, v83
	v_max_f32_e32 v178, v82, v82
	v_max_f32_e32 v0, v178, v0
	v_max3_f32 v0, v0, v84, v85
	v_max_f32_e32 v178, v98, v99
	v_max3_f32 v0, v0, v86, v87
	v_max3_f32 v178, v178, v100, v101
	v_max3_f32 v0, v0, v88, v89
	v_max3_f32 v178, v178, v102, v103
	v_max3_f32 v0, v0, v90, v91
	v_max3_f32 v178, v178, v104, v105
	v_max3_f32 v0, v0, v92, v93
	v_max3_f32 v178, v178, v106, v107
	v_max3_f32 v0, v0, v94, v95
	v_max3_f32 v178, v178, v108, v109
	v_max3_f32 v0, v0, v96, v97
	v_max3_f32 v178, v178, v110, v111
	v_max3_f32 v178, v178, v112, v113
	v_max_f32_e32 v0, v0, v178
	v_mov_b32_e32 v178, v0
	s_nop 1
	v_permlane32_swap_b32_e32 v0, v178
	v_add_f32_e32 v178, 0x41400000, v201
	v_cmp_lt_f32_e32 vcc, v178, v0
	s_cbranch_vccz .LBB0_569
	s_nop 0
	v_cndmask_b32_e32 v178, v201, v0, vcc
	v_cmp_neq_f32_e32 vcc, s53, v178
	s_nop 1
	v_cndmask_b32_e32 v0, 0, v178, vcc
	v_sub_f32_e32 v0, v201, v0
	v_exp_f32_e32 v0, v0
	v_mov_b32_e32 v201, v178
	v_mul_f32_e32 v32, v32, v0
	v_pk_mul_f32 v[80:81], v[80:81], v[0:1] op_sel_hi:[1,0]
	v_pk_mul_f32 v[78:79], v[78:79], v[0:1] op_sel_hi:[1,0]
	v_pk_mul_f32 v[76:77], v[76:77], v[0:1] op_sel_hi:[1,0]
	v_pk_mul_f32 v[74:75], v[74:75], v[0:1] op_sel_hi:[1,0]
	v_pk_mul_f32 v[72:73], v[72:73], v[0:1] op_sel_hi:[1,0]
	v_pk_mul_f32 v[70:71], v[70:71], v[0:1] op_sel_hi:[1,0]
	v_pk_mul_f32 v[68:69], v[68:69], v[0:1] op_sel_hi:[1,0]
	v_pk_mul_f32 v[66:67], v[66:67], v[0:1] op_sel_hi:[1,0]
	v_pk_mul_f32 v[64:65], v[64:65], v[0:1] op_sel_hi:[1,0]
	v_pk_mul_f32 v[62:63], v[62:63], v[0:1] op_sel_hi:[1,0]
	v_pk_mul_f32 v[60:61], v[60:61], v[0:1] op_sel_hi:[1,0]
	v_pk_mul_f32 v[58:59], v[58:59], v[0:1] op_sel_hi:[1,0]
	v_pk_mul_f32 v[56:57], v[56:57], v[0:1] op_sel_hi:[1,0]
	v_pk_mul_f32 v[54:55], v[54:55], v[0:1] op_sel_hi:[1,0]
	v_pk_mul_f32 v[52:53], v[52:53], v[0:1] op_sel_hi:[1,0]
	v_pk_mul_f32 v[50:51], v[50:51], v[0:1] op_sel_hi:[1,0]
	v_pk_mul_f32 v[48:49], v[48:49], v[0:1] op_sel_hi:[1,0]
	v_pk_mul_f32 v[46:47], v[46:47], v[0:1] op_sel_hi:[1,0]
	v_pk_mul_f32 v[44:45], v[44:45], v[0:1] op_sel_hi:[1,0]
	v_pk_mul_f32 v[42:43], v[42:43], v[0:1] op_sel_hi:[1,0]
	v_pk_mul_f32 v[40:41], v[40:41], v[0:1] op_sel_hi:[1,0]
	v_pk_mul_f32 v[38:39], v[38:39], v[0:1] op_sel_hi:[1,0]
	v_pk_mul_f32 v[36:37], v[36:37], v[0:1] op_sel_hi:[1,0]
	v_pk_mul_f32 v[34:35], v[34:35], v[0:1] op_sel_hi:[1,0]
	v_pk_mul_f32 v[30:31], v[30:31], v[0:1] op_sel_hi:[1,0]
	v_pk_mul_f32 v[28:29], v[28:29], v[0:1] op_sel_hi:[1,0]
	v_pk_mul_f32 v[26:27], v[26:27], v[0:1] op_sel_hi:[1,0]
	v_pk_mul_f32 v[24:25], v[24:25], v[0:1] op_sel_hi:[1,0]
	v_pk_mul_f32 v[22:23], v[22:23], v[0:1] op_sel_hi:[1,0]
	v_pk_mul_f32 v[20:21], v[20:21], v[0:1] op_sel_hi:[1,0]
	v_pk_mul_f32 v[18:19], v[18:19], v[0:1] op_sel_hi:[1,0]
	v_pk_mul_f32 v[16:17], v[16:17], v[0:1] op_sel_hi:[1,0]

; DI float fexp2(float x) { return __builtin_amdgcn_exp2f(x); }
; template <int MODE> DI void attn_h1(AttnCtx& c, const bf16x8 (&q)[8], f32x16 (&o)[4], f32x16& s0, f32x16& s1, ldsp lds, int kbuf, int bbuf, int tj, int lane) {
;     ...
;             if (MODE != MD_CMP2) {
;                 float mx = s0[0];
; #pragma unroll
;                 for (int e = 1; e < 16; ++e) mx = fmaxf(mx, s0[e]);
; #pragma unroll
;                 for (int e = 0; e < 16; ++e) mx = fmaxf(mx, s1[e]);
;                 { typedef unsigned u2_t __attribute__((ext_vector_type(2)));
;                   const unsigned mb = __builtin_bit_cast(unsigned, mx);
;                   const u2_t sw = __builtin_amdgcn_permlane32_swap(mb, mb, false, false);
;                   mx = fmaxf(__builtin_bit_cast(float, sw.x), __builtin_bit_cast(float, sw.y)); }
;                 const bool need = mx > c.m + 12.0f;
;                 if (__ballot(need) != 0ull) {
;                     const float mnew = need ? mx : c.m;
;                     const float alpha = fexp2(c.m - ((mnew == NINF) ? 0.f : mnew));
;                     c.l *= alpha; c.m = mnew;
;                     if (MODE != MD_CMP1) {
; #pragma unroll
;                         for (int db = 0; db < 4; ++db)
; #pragma unroll
;                             for (int e = 0; e < 16; ++e) o[db][e] *= alpha;
;                     }
;                 }
; template <int MODE> DI void attn_h2(AttnCtx& c, f32x16 (&o)[4], f32x16& s0, f32x16& s1, ldsp lds, int vbuf, int tj, int lane) {
;     ...
;             } else {
;                 const float muse = (c.m == NINF) ? 0.f : c.m;
;                 float ps = 0.f;
; #pragma unroll
;                 for (int e = 0; e < 16; ++e) { s0[e] = fexp2(s0[e] - muse); s1[e] = fexp2(s1[e] - muse); ps += s0[e] + s1[e]; }
;                 c.l += ps;
;                         }
;             if (MODE != MD_CMP1) {
;                 ldsp vl = lds + vbuf + r32 * VPITCH + 16 * h;
; #pragma unroll
;                 for (int kb = 0; kb < 2; ++kb)
; #pragma unroll
;                     for (int s2 = 0; s2 < 2; ++s2) {
;                         u32x4 pw;
;                         if (kb == 0) { pw.x = pk2(s0[8 * s2], s0[8 * s2 + 1]); pw.y = pk2(s0[8 * s2 + 2], s0[8 * s2 + 3]); pw.z = pk2(s0[8 * s2 + 4], s0[8 * s2 + 5]); pw.w = pk2(s0[8 * s2 + 6], s0[8 * s2 + 7]); }
.LBB0_891:
	v_max_f32_e32 v2, v62, v62
	v_max_f32_e32 v3, v0, v0
	v_max_f32_e32 v2, v3, v2
	v_max3_f32 v2, v2, v34, v35
	v_max_f32_e32 v3, v36, v37
	v_max3_f32 v2, v2, v40, v41
	v_max3_f32 v3, v3, v42, v43
	v_max3_f32 v2, v2, v44, v45
	v_max3_f32 v3, v3, v50, v51
	v_max3_f32 v2, v2, v52, v53
	v_max3_f32 v3, v3, v54, v55
	v_max3_f32 v2, v2, v56, v57
	v_max3_f32 v3, v3, v58, v59
	v_max3_f32 v2, v2, v38, v39
	v_max3_f32 v3, v3, v60, v61
	v_max3_f32 v2, v2, v46, v47
	v_max3_f32 v3, v3, v48, v49
	v_max3_f32 v3, v3, v83, v84
	v_max_f32_e32 v2, v2, v3
	v_mov_b32_e32 v3, v2
	s_nop 1
	v_permlane32_swap_b32_e32 v2, v3
	v_cmp_lg_f32_e32 vcc, s53, v2
	s_nop 1
	v_cndmask_b32_e32 v3, v230, v2, vcc
	v_sub_f32_e32 v4, 0xff800000, v3
	v_cmp_neq_f32_e32 vcc, s53, v3
	s_nop 1
	v_cndmask_b32_e32 v4, v230, v4, vcc
	v_exp_f32_e32 v4, v4
	v_cmp_neq_f32_e32 vcc, s53, v2
	s_cmp_eq_u64 vcc, 0
	s_cselect_b64 vcc, -1, 0
	v_mul_f32_e32 v2, 0, v4
	v_cndmask_b32_e32 v155, v3, v230, vcc
	v_cndmask_b32_e64 v18, v2, 0, vcc
	v_cmp_neq_f32_e32 vcc, s53, v155
	v_mov_b32_e32 v19, v18
	v_mov_b32_e32 v20, v18
	v_cndmask_b32_e32 v85, 0, v155, vcc
	v_sub_f32_e32 v0, v0, v85
	v_exp_f32_e32 v63, v0
	v_sub_f32_e32 v0, v36, v85
	v_exp_f32_e32 v166, v0
	v_sub_f32_e32 v0, v62, v85
	v_exp_f32_e32 v36, v0
	v_sub_f32_e32 v0, v37, v85
	v_exp_f32_e32 v0, v0
	v_add_f32_e32 v37, v63, v166
	v_mov_b32_e32 v21, v18
	v_mov_b32_e32 v22, v18
	v_pk_add_f32 v[2:3], v[36:37], v[0:1]
	v_mov_b32_e32 v23, v18
	v_pk_add_f32 v[2:3], v[2:3], v[2:3] op_sel_hi:[0,1]
	v_sub_f32_e32 v2, v34, v85
	v_exp_f32_e32 v37, v2
	v_sub_f32_e32 v2, v42, v85
	v_exp_f32_e32 v167, v2
	v_sub_f32_e32 v2, v35, v85
	v_exp_f32_e32 v34, v2
	v_sub_f32_e32 v2, v43, v85
	v_exp_f32_e32 v2, v2
	v_add_f32_e32 v35, v37, v167
	v_mov_b32_e32 v24, v18
	v_mov_b32_e32 v25, v18
	v_pk_add_f32 v[4:5], v[34:35], v[2:3]
	v_sub_f32_e32 v3, v40, v85
	v_pk_add_f32 v[6:7], v[4:5], v[4:5] op_sel_hi:[0,1]
	v_sub_f32_e32 v4, v50, v85
	v_exp_f32_e32 v168, v4
	v_sub_f32_e32 v4, v41, v85
	v_exp_f32_e32 v3, v3
	v_exp_f32_e32 v40, v4
	v_sub_f32_e32 v4, v51, v85
	v_exp_f32_e32 v6, v4
	v_add_f32_e32 v41, v3, v168
	v_mov_b32_e32 v26, v18
	v_mov_b32_e32 v27, v18
	v_pk_add_f32 v[4:5], v[40:41], v[6:7]
	v_mov_b32_e32 v28, v18
	v_pk_add_f32 v[10:11], v[4:5], v[4:5] op_sel_hi:[0,1]
	v_sub_f32_e32 v4, v44, v85
	v_exp_f32_e32 v7, v4
	v_sub_f32_e32 v4, v54, v85
	v_exp_f32_e32 v169, v4
	v_sub_f32_e32 v4, v45, v85
	v_exp_f32_e32 v42, v4
	v_sub_f32_e32 v4, v55, v85
	v_exp_f32_e32 v10, v4
	v_add_f32_e32 v43, v7, v169
	v_mov_b32_e32 v29, v18
	v_mov_b32_e32 v30, v18
	v_pk_add_f32 v[4:5], v[42:43], v[10:11]
	v_mov_b32_e32 v31, v18
	v_pk_add_f32 v[4:5], v[4:5], v[4:5] op_sel_hi:[0,1]
	v_sub_f32_e32 v4, v52, v85
	v_exp_f32_e32 v11, v4
	v_sub_f32_e32 v4, v58, v85
	v_exp_f32_e32 v170, v4
	v_sub_f32_e32 v4, v53, v85
	v_exp_f32_e32 v160, v4
	v_sub_f32_e32 v4, v59, v85
	v_exp_f32_e32 v4, v4
	v_add_f32_e32 v161, v11, v170
	v_mov_b32_e32 v32, v18
	v_mov_b32_e32 v33, v18
	v_pk_add_f32 v[8:9], v[160:161], v[4:5]
	v_sub_f32_e32 v5, v56, v85
	v_pk_add_f32 v[8:9], v[8:9], v[8:9] op_sel_hi:[0,1]
	v_sub_f32_e32 v8, v60, v85
	v_exp_f32_e32 v161, v8
	v_sub_f32_e32 v8, v57, v85
	v_exp_f32_e32 v5, v5
	v_exp_f32_e32 v162, v8
	v_sub_f32_e32 v8, v61, v85
	v_exp_f32_e32 v8, v8
	v_add_f32_e32 v163, v5, v161
	v_cvt_pk_bf16_f32 v86, v63, v36
	v_cvt_pk_bf16_f32 v87, v37, v34
	v_pk_add_f32 v[12:13], v[162:163], v[8:9]
	v_add_u32_e32 v163, v206, v82
	ds_read_b128 v[14:17], v163 offset:34816
	ds_read_b128 v[34:37], v163 offset:39424
	v_pk_add_f32 v[12:13], v[12:13], v[12:13] op_sel_hi:[0,1]
	v_sub_f32_e32 v12, v48, v85
	v_sub_f32_e32 v9, v38, v85
	v_exp_f32_e32 v171, v12
	v_sub_f32_e32 v12, v39, v85
	v_exp_f32_e32 v9, v9
	v_exp_f32_e32 v164, v12
	v_sub_f32_e32 v12, v49, v85
	v_exp_f32_e32 v12, v12
	v_cvt_pk_bf16_f32 v88, v3, v40
	v_cvt_pk_bf16_f32 v89, v7, v42
	v_add_f32_e32 v165, v9, v171
	ds_read_b128 v[90:93], v163 offset:44032
	ds_read_b128 v[94:97], v163 offset:48640
	s_waitcnt lgkmcnt(3)
	v_mfma_f32_32x32x16_bf16 v[66:81], v[14:17], v[86:89], v[18:33]
	v_add_f32_e64 v14, v164, v12
	v_add_f32_e64 v15, v165, v13
	v_sub_f32_e32 v3, v46, v85
	v_sub_f32_e32 v7, v83, v85
	v_sub_f32_e32 v13, v47, v85
	v_pk_add_f32 v[14:15], v[14:15], v[14:15] op_sel_hi:[0,1]
	v_exp_f32_e32 v3, v3
	v_exp_f32_e32 v7, v7
	v_exp_f32_e32 v16, v13
	v_sub_f32_e32 v13, v84, v85
	v_exp_f32_e32 v14, v13
	v_add_f32_e32 v17, v3, v7
	s_waitcnt lgkmcnt(2)
	v_mfma_f32_32x32x16_bf16 v[50:65], v[34:37], v[86:89], v[18:33]
	v_add_f32_e64 v84, v16, v14
	v_add_f32_e64 v85, v17, v15
	v_add_f32_e32 v13, v84, v85
	v_add_f32_e32 v210, v18, v13
	s_waitcnt lgkmcnt(1)
	v_mfma_f32_32x32x16_bf16 v[34:49], v[90:93], v[86:89], v[18:33]
	v_cvt_pk_bf16_f32 v90, v9, v164
	v_cvt_pk_bf16_f32 v91, v3, v16
	v_cvt_pk_bf16_f32 v3, v161, v8
	s_waitcnt lgkmcnt(0)
	v_mfma_f32_32x32x16_bf16 v[18:33], v[94:97], v[86:89], v[18:33]
	ds_read_b128 v[84:87], v163 offset:34848
	v_cvt_pk_bf16_f32 v88, v11, v160
	v_cvt_pk_bf16_f32 v89, v5, v162
	v_cvt_pk_bf16_f32 v5, v7, v14
	s_waitcnt lgkmcnt(0)
	v_mfma_f32_32x32x16_bf16 v[66:81], v[84:87], v[88:91], v[66:81]
	ds_read_b128 v[84:87], v163 offset:39456
	s_waitcnt lgkmcnt(0)
	v_mfma_f32_32x32x16_bf16 v[50:65], v[84:87], v[88:91], v[50:65]
	ds_read_b128 v[84:87], v163 offset:44064
	s_waitcnt lgkmcnt(0)
	v_mfma_f32_32x32x16_bf16 v[34:49], v[84:87], v[88:91], v[34:49]
	ds_read_b128 v[84:87], v163 offset:48672
	s_waitcnt lgkmcnt(0)
	v_mfma_f32_32x32x16_bf16 v[18:33], v[84:87], v[88:91], v[18:33]
	ds_read_b128 v[84:87], v163 offset:34880
	v_cvt_pk_bf16_f32 v88, v166, v0
	v_cvt_pk_bf16_f32 v89, v167, v2
	v_cvt_pk_bf16_f32 v90, v168, v6
	v_cvt_pk_bf16_f32 v91, v169, v10
	ds_read_b128 v[6:9], v163 offset:39520
	v_cvt_pk_bf16_f32 v2, v170, v4
	s_waitcnt lgkmcnt(1)
	v_mfma_f32_32x32x16_bf16 v[66:81], v[84:87], v[88:91], v[66:81]
	ds_read_b128 v[84:87], v163 offset:39488
	v_cvt_pk_bf16_f32 v4, v171, v12
	s_waitcnt lgkmcnt(0)
	v_mfma_f32_32x32x16_bf16 v[50:65], v[84:87], v[88:91], v[50:65]
	ds_read_b128 v[84:87], v163 offset:44096
	s_waitcnt lgkmcnt(0)
	v_mfma_f32_32x32x16_bf16 v[34:49], v[84:87], v[88:91], v[34:49]
	ds_read_b128 v[84:87], v163 offset:48704
	s_waitcnt lgkmcnt(0)
	v_mfma_f32_32x32x16_bf16 v[18:33], v[84:87], v[88:91], v[18:33]
	ds_read_b128 v[84:87], v163 offset:34912
	v_mfma_f32_32x32x16_bf16 v[50:65], v[6:9], v[2:5], v[50:65]
	ds_read_b128 v[6:9], v163 offset:44128
	s_waitcnt lgkmcnt(0)
	v_mfma_f32_32x32x16_bf16 v[34:49], v[6:9], v[2:5], v[34:49]
	ds_read_b128 v[6:9], v163 offset:48736
	v_mfma_f32_32x32x16_bf16 v[66:81], v[84:87], v[2:5], v[66:81]
	s_waitcnt lgkmcnt(0)
	v_mfma_f32_32x32x16_bf16 v[18:33], v[6:9], v[2:5], v[18:33]
	s_and_b64 vcc, exec, s[2:3]
	s_cbranch_vccnz .LBB0_893

; DI float fexp2(float x) { return __builtin_amdgcn_exp2f(x); }
; template <int MODE> DI void attn_h1(AttnCtx& c, const bf16x8 (&q)[8], f32x16 (&o)[4], f32x16& s0, f32x16& s1, ldsp lds, int kbuf, int bbuf, int tj, int lane) {
;     ...
;             if (MODE != MD_CMP2) {
;                 float mx = s0[0];
; #pragma unroll
;                 for (int e = 1; e < 16; ++e) mx = fmaxf(mx, s0[e]);
; #pragma unroll
;                 for (int e = 0; e < 16; ++e) mx = fmaxf(mx, s1[e]);
;                 { typedef unsigned u2_t __attribute__((ext_vector_type(2)));
;                   const unsigned mb = __builtin_bit_cast(unsigned, mx);
;                   const u2_t sw = __builtin_amdgcn_permlane32_swap(mb, mb, false, false);
;                   mx = fmaxf(__builtin_bit_cast(float, sw.x), __builtin_bit_cast(float, sw.y)); }
;                 const bool need = mx > c.m + 12.0f;
;                 if (__ballot(need) != 0ull) {
;                     const float mnew = need ? mx : c.m;
;                     const float alpha = fexp2(c.m - ((mnew == NINF) ? 0.f : mnew));
;                     c.l *= alpha; c.m = mnew;
;                     if (MODE != MD_CMP1) {
; #pragma unroll
;                         for (int db = 0; db < 4; ++db)
; #pragma unroll
;                             for (int e = 0; e < 16; ++e) o[db][e] *= alpha;
;                     }
;                 }
.LBB0_915:
	v_max_f32_e32 v2, v216, v216
	v_max_f32_e32 v3, v0, v0
	v_max_f32_e32 v2, v3, v2
	v_max3_f32 v2, v2, v180, v181
	v_max_f32_e32 v3, v184, v185
	v_max3_f32 v2, v2, v182, v183
	v_max3_f32 v3, v3, v186, v187
	v_max3_f32 v2, v2, v178, v179
	v_max3_f32 v3, v3, v172, v173
	v_max3_f32 v2, v2, v168, v169
	v_max3_f32 v3, v3, v164, v165
	v_max3_f32 v2, v2, v170, v171
	v_max3_f32 v3, v3, v166, v167
	v_max3_f32 v2, v2, v174, v175
	v_max3_f32 v3, v3, v160, v161
	v_max3_f32 v2, v2, v176, v177
	v_max3_f32 v3, v3, v162, v163
	v_max3_f32 v3, v3, v214, v215
	v_max_f32_e32 v2, v2, v3
	v_mov_b32_e32 v3, v2
	s_nop 1
	v_permlane32_swap_b32_e32 v2, v3
	v_add_f32_e32 v3, 0x41400000, v155
	v_cmp_lt_f32_e32 vcc, v3, v2
	s_cbranch_vccz .LBB0_917
	s_nop 0
	v_cndmask_b32_e32 v3, v155, v2, vcc
	v_cmp_neq_f32_e32 vcc, s53, v3
	s_nop 1
	v_cndmask_b32_e32 v2, 0, v3, vcc
	v_sub_f32_e32 v2, v155, v2
	v_exp_f32_e32 v2, v2
	v_mov_b32_e32 v155, v3
	v_mul_f32_e32 v210, v210, v2
	v_pk_mul_f32 v[80:81], v[80:81], v[2:3] op_sel_hi:[1,0]
	v_pk_mul_f32 v[78:79], v[78:79], v[2:3] op_sel_hi:[1,0]
	v_pk_mul_f32 v[76:77], v[76:77], v[2:3] op_sel_hi:[1,0]
	v_pk_mul_f32 v[74:75], v[74:75], v[2:3] op_sel_hi:[1,0]
	v_pk_mul_f32 v[72:73], v[72:73], v[2:3] op_sel_hi:[1,0]
	v_pk_mul_f32 v[70:71], v[70:71], v[2:3] op_sel_hi:[1,0]
	v_pk_mul_f32 v[68:69], v[68:69], v[2:3] op_sel_hi:[1,0]
	v_pk_mul_f32 v[66:67], v[66:67], v[2:3] op_sel_hi:[1,0]
	v_pk_mul_f32 v[64:65], v[64:65], v[2:3] op_sel_hi:[1,0]
	v_pk_mul_f32 v[62:63], v[62:63], v[2:3] op_sel_hi:[1,0]
	v_pk_mul_f32 v[60:61], v[60:61], v[2:3] op_sel_hi:[1,0]
	v_pk_mul_f32 v[58:59], v[58:59], v[2:3] op_sel_hi:[1,0]
	v_pk_mul_f32 v[56:57], v[56:57], v[2:3] op_sel_hi:[1,0]
	v_pk_mul_f32 v[54:55], v[54:55], v[2:3] op_sel_hi:[1,0]
	v_pk_mul_f32 v[52:53], v[52:53], v[2:3] op_sel_hi:[1,0]
	v_pk_mul_f32 v[50:51], v[50:51], v[2:3] op_sel_hi:[1,0]
	v_pk_mul_f32 v[48:49], v[48:49], v[2:3] op_sel_hi:[1,0]
	v_pk_mul_f32 v[46:47], v[46:47], v[2:3] op_sel_hi:[1,0]
	v_pk_mul_f32 v[44:45], v[44:45], v[2:3] op_sel_hi:[1,0]
	v_pk_mul_f32 v[42:43], v[42:43], v[2:3] op_sel_hi:[1,0]
	v_pk_mul_f32 v[40:41], v[40:41], v[2:3] op_sel_hi:[1,0]
	v_pk_mul_f32 v[38:39], v[38:39], v[2:3] op_sel_hi:[1,0]
	v_pk_mul_f32 v[36:37], v[36:37], v[2:3] op_sel_hi:[1,0]
	v_pk_mul_f32 v[34:35], v[34:35], v[2:3] op_sel_hi:[1,0]
	v_pk_mul_f32 v[32:33], v[32:33], v[2:3] op_sel_hi:[1,0]
	v_pk_mul_f32 v[30:31], v[30:31], v[2:3] op_sel_hi:[1,0]
	v_pk_mul_f32 v[28:29], v[28:29], v[2:3] op_sel_hi:[1,0]
	v_pk_mul_f32 v[26:27], v[26:27], v[2:3] op_sel_hi:[1,0]
	v_pk_mul_f32 v[24:25], v[24:25], v[2:3] op_sel_hi:[1,0]
	v_pk_mul_f32 v[22:23], v[22:23], v[2:3] op_sel_hi:[1,0]
	v_pk_mul_f32 v[20:21], v[20:21], v[2:3] op_sel_hi:[1,0]
	v_pk_mul_f32 v[18:19], v[18:19], v[2:3] op_sel_hi:[1,0]

; DI float fexp2(float x) { return __builtin_amdgcn_exp2f(x); }
; template <int MODE> DI void attn_h1(AttnCtx& c, const bf16x8 (&q)[8], f32x16 (&o)[4], f32x16& s0, f32x16& s1, ldsp lds, int kbuf, int bbuf, int tj, int lane) {
;     ...
;             if (MODE != MD_CMP2) {
;                 float mx = s0[0];
; #pragma unroll
;                 for (int e = 1; e < 16; ++e) mx = fmaxf(mx, s0[e]);
; #pragma unroll
;                 for (int e = 0; e < 16; ++e) mx = fmaxf(mx, s1[e]);
;                 { typedef unsigned u2_t __attribute__((ext_vector_type(2)));
;                   const unsigned mb = __builtin_bit_cast(unsigned, mx);
;                   const u2_t sw = __builtin_amdgcn_permlane32_swap(mb, mb, false, false);
;                   mx = fmaxf(__builtin_bit_cast(float, sw.x), __builtin_bit_cast(float, sw.y)); }
;                 const bool need = mx > c.m + 12.0f;
;                 if (__ballot(need) != 0ull) {
;                     const float mnew = need ? mx : c.m;
;                     const float alpha = fexp2(c.m - ((mnew == NINF) ? 0.f : mnew));
;                     c.l *= alpha; c.m = mnew;
;                     if (MODE != MD_CMP1) {
; #pragma unroll
;                         for (int db = 0; db < 4; ++db)
; #pragma unroll
;                             for (int e = 0; e < 16; ++e) o[db][e] *= alpha;
;                     }
;                 }
.LBB0_1070:
	v_max_f32_e32 v66, v177, v177
	v_max_f32_e32 v67, v82, v82
	v_max_f32_e32 v66, v67, v66
	v_max3_f32 v66, v66, v148, v149
	v_max_f32_e32 v67, v154, v155
	v_max3_f32 v66, v66, v160, v161
	v_max3_f32 v67, v67, v162, v163
	v_max3_f32 v66, v66, v166, v167
	v_max3_f32 v67, v67, v164, v165
	v_max3_f32 v66, v66, v170, v171
	v_max3_f32 v67, v67, v168, v169
	v_max3_f32 v66, v66, v174, v175
	v_max3_f32 v67, v67, v172, v173
	v_max3_f32 v66, v66, v180, v181
	v_max3_f32 v67, v67, v178, v179
	v_max3_f32 v66, v66, v184, v185
	v_max3_f32 v67, v67, v182, v183
	v_max3_f32 v67, v67, v199, v200
	v_max_f32_e32 v66, v66, v67
	v_mov_b32_e32 v67, v66
	s_nop 1
	v_permlane32_swap_b32_e32 v66, v67
	v_add_f32_e32 v67, 0x41400000, v186
	v_cmp_lt_f32_e32 vcc, v67, v66
	s_cbranch_vccz .LBB0_1072
	s_nop 0
	v_cndmask_b32_e32 v67, v186, v66, vcc
	v_cmp_neq_f32_e32 vcc, s53, v67
	s_nop 1
	v_cndmask_b32_e32 v66, 0, v67, vcc
	v_sub_f32_e32 v66, v186, v66
	v_exp_f32_e32 v66, v66
	v_mov_b32_e32 v186, v67
	v_mul_f32_e32 v190, v190, v66
	v_pk_mul_f32 v[64:65], v[64:65], v[66:67] op_sel_hi:[1,0]
	v_pk_mul_f32 v[62:63], v[62:63], v[66:67] op_sel_hi:[1,0]
	v_pk_mul_f32 v[60:61], v[60:61], v[66:67] op_sel_hi:[1,0]
	v_pk_mul_f32 v[58:59], v[58:59], v[66:67] op_sel_hi:[1,0]
	v_pk_mul_f32 v[56:57], v[56:57], v[66:67] op_sel_hi:[1,0]
	v_pk_mul_f32 v[54:55], v[54:55], v[66:67] op_sel_hi:[1,0]
	v_pk_mul_f32 v[52:53], v[52:53], v[66:67] op_sel_hi:[1,0]
	v_pk_mul_f32 v[50:51], v[50:51], v[66:67] op_sel_hi:[1,0]
	v_pk_mul_f32 v[48:49], v[48:49], v[66:67] op_sel_hi:[1,0]
	v_pk_mul_f32 v[46:47], v[46:47], v[66:67] op_sel_hi:[1,0]
	v_pk_mul_f32 v[44:45], v[44:45], v[66:67] op_sel_hi:[1,0]
	v_pk_mul_f32 v[42:43], v[42:43], v[66:67] op_sel_hi:[1,0]
	v_pk_mul_f32 v[40:41], v[40:41], v[66:67] op_sel_hi:[1,0]
	v_pk_mul_f32 v[38:39], v[38:39], v[66:67] op_sel_hi:[1,0]
	v_pk_mul_f32 v[36:37], v[36:37], v[66:67] op_sel_hi:[1,0]
	v_pk_mul_f32 v[34:35], v[34:35], v[66:67] op_sel_hi:[1,0]
	v_pk_mul_f32 v[32:33], v[32:33], v[66:67] op_sel_hi:[1,0]
	v_pk_mul_f32 v[30:31], v[30:31], v[66:67] op_sel_hi:[1,0]
	v_pk_mul_f32 v[28:29], v[28:29], v[66:67] op_sel_hi:[1,0]
	v_pk_mul_f32 v[26:27], v[26:27], v[66:67] op_sel_hi:[1,0]
	v_pk_mul_f32 v[24:25], v[24:25], v[66:67] op_sel_hi:[1,0]
	v_pk_mul_f32 v[22:23], v[22:23], v[66:67] op_sel_hi:[1,0]
	v_pk_mul_f32 v[20:21], v[20:21], v[66:67] op_sel_hi:[1,0]
	v_pk_mul_f32 v[18:19], v[18:19], v[66:67] op_sel_hi:[1,0]
	v_pk_mul_f32 v[16:17], v[16:17], v[66:67] op_sel_hi:[1,0]
	v_pk_mul_f32 v[14:15], v[14:15], v[66:67] op_sel_hi:[1,0]
	v_pk_mul_f32 v[12:13], v[12:13], v[66:67] op_sel_hi:[1,0]
	v_pk_mul_f32 v[10:11], v[10:11], v[66:67] op_sel_hi:[1,0]
	v_pk_mul_f32 v[8:9], v[8:9], v[66:67] op_sel_hi:[1,0]
	v_pk_mul_f32 v[6:7], v[6:7], v[66:67] op_sel_hi:[1,0]
	v_pk_mul_f32 v[4:5], v[4:5], v[66:67] op_sel_hi:[1,0]
	v_pk_mul_f32 v[2:3], v[2:3], v[66:67] op_sel_hi:[1,0]
